# nb8b: no grid barrier 8 - piece waves signal a per-XCD counter; wave 0 of WG 128..135 flushes its XCD L2 mid-unit (before any y store) and bumps a device word; non-piece WGs poll it after their unit a
# speedup vs baseline: 1.0147x; 1.0147x over previous
; __global__ void __launch_bounds__(512, 2) fwd_megakernel(Params P) {
;     ...
;     xcd_barrier(bar);
;     { FRESH_IDS; final_norm(P, G, wave, lane, P.out + O_Y); }
.Lsp7_h:
	s_cmp_eq_u32 s101, 0x8888
	s_cbranch_scc1 .Lnb8_h
	s_cmp_eq_u32 s101, 0x9999
	s_cbranch_scc1 .Lnb8_c
	s_cmp_eq_u32 s73, 4
	s_cbranch_scc0 .Lsp7_h2
	s_mov_b64 exec, 1
	s_lshl_b32 s98, s33, 8
	s_add_u32 s98, s98, 0x82400
	v_mov_b32_e32 v246, s98
	global_load_dword v247, v246, s[68:69] sc1
	s_mov_b64 exec, -1
	s_branch .Lsp7_back

; __global__ void __launch_bounds__(512, 2) fwd_megakernel(Params P) {
;     ...
;     xcd_barrier(bar);
;     { FRESH_IDS; final_norm(P, G, wave, lane, P.out + O_Y); }
.Lnb8_c:
	s_cmp_eq_u32 s73, 32
	s_cbranch_scc0 .Lsp7_back
	s_mov_b64 exec, 1
	s_lshl_b32 s98, s33, 8
	s_add_u32 s98, s98, 0x54000
	v_mov_b32_e32 v246, s98
	s_mov_b32 s98, 0x10000
.Lnb8_cp:
	global_load_dword v247, v246, s[68:69] sc1
	s_waitcnt vmcnt(0)
	v_cmp_eq_u32_e32 vcc, 0x80, v247
	s_cbranch_vccnz .Lnb8_cf
	s_sleep 1
	s_sub_u32 s98, s98, 1
	s_cmp_lg_u32 s98, 0
	s_cbranch_scc1 .Lnb8_cp
.Lnb8_cf:
	buffer_wbl2 sc1
	s_waitcnt vmcnt(0)
	v_mov_b32_e32 v246, 0x54800
	v_mov_b32_e32 v247, 1
	global_atomic_add v246, v247, s[68:69]
	s_mov_b32 s99, 0
	s_mov_b32 s101, 0
	s_mov_b64 exec, -1
	s_branch .Lsp7_back

;     __host__ __device__ bool next(int i, Unit& u) const { return at((long)i * G + c, u); }
;     __host__ __device__ bool next(int i, Unit& u) const { if (i != 0 || c >= cnt) return false; u.pm = pm0 + c / nN; u.pn = c % nN; u.k0 = 0; u.nt = ntk; return true; }
;     ...
;         const bool has_next = S.next(ui + 1, nxt);
;         const char* nA = has_next ? (const char*)g.A + (size_t)nxt.pm * tstep + (size_t)nxt.k0 * (BK * 2) : cA; const char* nB = has_next ? (const char*)g.Bt + (size_t)nxt.pn * tstep + (size_t)nxt.k0 * (BK * 2) : cB;
;         const int nt = cur.nt;
;         for (int t = 0; t < nt; t += 2) {
;             const bool last = (t == nt - 2);
;             const char* a1 = cA + (size_t)(t + 1) * kstep;
;             const char* a2 = last ? nA : cA + (size_t)(t + 2) * kstep; const char* b2 = last ? nB : cB + (size_t)(t + 2) * kstep;
;             const char* a3 = a2 + kstep; const char* b3 = b2 + kstep;
;             if (last && has_next) S.a_ready(nxt);
.LBB0_1053:
	s_ashr_i32 s23, s22, 31
	s_xor_b64 s[28:29], s[40:41], -1
	s_lshl_b64 s[30:31], s[22:23], 21
	s_add_u32 s13, s4, s30
	s_addc_u32 s23, s5, s31
	s_ashr_i32 s27, s26, 31
	s_lshl_b64 s[34:35], s[26:27], 7
	s_add_u32 s30, s13, s34
	s_addc_u32 s31, s23, s35
	s_and_b64 s[42:43], s[40:41], exec
	s_cselect_b32 s13, s31, s39
	s_cselect_b32 s23, s30, s38
	s_ashr_i32 s25, s24, 31
	s_lshl_b64 s[42:43], s[24:25], 21
	s_add_u32 s25, s3, s42
	s_addc_u32 s27, s47, s43
	s_add_u32 s34, s25, s34
	s_addc_u32 s35, s27, s35
	s_and_b64 s[42:43], s[40:41], exec
	s_cselect_b32 s25, s35, s37
	s_cselect_b32 s27, s34, s36
	s_mov_b32 s73, 2
	s_mov_b64 s[42:43], 0x100
	v_mov_b64_e32 v[130:131], v[144:145]
	v_mov_b64_e32 v[150:151], v[142:143]
	s_cmp_lg_u32 s100, 0
	s_cbranch_scc1 .Lnb8_m
	v_readlane_b32 s98, v255, 14
	s_lshr_b32 s98, s98, 6
	s_cmp_lg_u32 s98, 16
	s_cbranch_scc1 .Lnb8_m
	v_readlane_b32 s98, v255, 13
	s_cmp_lg_u32 s98, 0
	s_cbranch_scc1 .Lnb8_m
	s_mov_b32 s99, 0x7777
	s_mov_b32 s101, 0x9999
.Lnb8_m:
	v_readlane_b32 s98, v255, 17
	s_cmp_lg_u32 s98, 1
	s_cbranch_scc1 .Lsprio_6
	s_setprio 1

; __global__ void __launch_bounds__(512, 2) fwd_megakernel(Params P) {
;     ...
;     xcd_barrier(bar);
;     { FRESH_IDS; final_norm(P, G, wave, lane, P.out + O_Y); }
.LBB0_1102:
	s_cmp_lg_u32 s100, 0
	s_cbranch_scc1 .Lnb8_norm
	v_readlane_b32 s98, v255, 14
	s_cmpk_lt_u32 s98, 0x400
	s_cbranch_scc1 .LBB0_1157
	v_readlane_b32 s99, v255, 13
	s_sub_u32 s98, s98, 0x400
	s_add_u32 s64, s98, s99
	s_cmp_lg_u32 s99, 0
	s_cbranch_scc1 .Lnb8_wait
	s_mov_b64 exec, 1
	s_lshl_b32 s98, s33, 8
	s_add_u32 s98, s98, 0x54000
	v_mov_b32_e32 v0, s98
	v_mov_b32_e32 v1, 1
	v_mov_b32_e32 v3, 0x54800
	s_mov_b32 s98, 0x10000
